# out epilogue (layers 1-3): accumulators transposed through a wave-private LDS scratch so residual loads/stores use a line-major lane mapping (8 lanes per 128B line) instead of the MFMA C layout
# speedup vs baseline: 1.0081x; 1.0034x over previous
; #define PG8_STAGE(bufoff, gbase, voff) do { _Pragma("unroll") for (int _i = 0; _i < 2; ++_i) \
;         __builtin_amdgcn_global_load_lds((const unsigned*)((const char*)(gbase) + (voff)[_i]), (PG8_LAS unsigned*)(lds + (bufoff) + ldsw + _i * 8192), 16, 0, 0); } while (0)
; #define PG8_LDA(dst, b, h) do { _Pragma("unroll") for (int m = 0; m < 4; ++m) _Pragma("unroll") for (int k = 0; k < 2; ++k) dst[m][k] = *(const PG8_LAS bf16x8*)(lds + PG8_SA(b, h) + aoff + m * 2048 + k * 1024); } while (0)
; #define PG8_LDB(dst, b, h) do { _Pragma("unroll") for (int n = 0; n < 2; ++n) _Pragma("unroll") for (int k = 0; k < 2; ++k) dst[n][k] = *(const PG8_LAS bf16x8*)(lds + PG8_SB(b, h) + boff + n * 2048 + k * 1024); } while (0)
; #define PG8_MMA(ai, bj, At, Bt) do { __builtin_amdgcn_s_setprio(1); _Pragma("unroll") for (int m = 0; m < 4; ++m) _Pragma("unroll") for (int n = 0; n < 2; ++n) _Pragma("unroll") for (int k = 0; k < 2; ++k) \
;         acc[ai][bj][m][n] = __builtin_amdgcn_mfma_f32_16x16x32_bf16(Bt[n][k], At[m][k], acc[ai][bj][m][n], 0, 0, 0); __builtin_amdgcn_s_setprio(0); } while (0)
; #define PG8_WAIT_L(n) asm volatile("s_waitcnt lgkmcnt(" #n ")" ::: "memory")
; #define PG8_BAR __builtin_amdgcn_s_barrier()
; #define PG8_SCHED __builtin_amdgcn_sched_barrier(0)
; template <class Epi, class Sched>
; __device__ __forceinline__ void gemm_phase(PG8_LAS unsigned char* lds, const Gemm g, const Sched& S, const Epi& E) {
;     ...
;             PG8_LDB(B0, 0, 0); PG8_SCHED; PG8_LDA(At, 0, 0); PG8_STAGE(PG8_SA(1, 1), a1 + hstep, voffA);
;             PG8_WAIT_L(8); PG8_BAR; PG8_WAIT_L(0); PG8_MMA(0, 0, At, B0); PG8_BAR; PG8_SCHED;
;             PG8_LDB(B1, 0, 1); PG8_STAGE(PG8_SB(0, 0), b2, voffB);
;             PG8_BAR; PG8_WAIT_L(0); PG8_MMA(0, 1, At, B1); PG8_BAR;
;             PG8_LDA(At, 0, 1); PG8_STAGE(PG8_SA(0, 0), a2, voffA);
;             PG8_BAR; PG8_WAIT_L(0); PG8_MMA(1, 0, At, B0); PG8_BAR; PG8_SCHED;
.LBB0_2754:
	s_add_u32 s14, s12, 0xfffc0080
	s_addc_u32 s15, s13, -1
	s_add_i32 s37, 0, 0x10000
	v_add_u32_e32 v140, s37, v142
	ds_read_b128 v[144:147], v140
	ds_read_b128 v[148:151], v140 offset:1024
	ds_read_b128 v[162:165], v140 offset:2048
	ds_read_b128 v[166:169], v140 offset:3072
	s_cmp_eq_u32 s36, 12
	s_cselect_b32 s17, s5, s15
	s_cselect_b32 s16, s31, s14
	s_cselect_b32 s15, s3, s35
	s_cselect_b32 s14, s33, s34
	v_lshl_add_u64 v[140:141], s[12:13], 0, v[136:137]
	s_add_i32 m0, s23, 0xc000
	ds_read_b128 v[170:173], v143
	ds_read_b128 v[174:177], v143 offset:1024
	ds_read_b128 v[178:181], v143 offset:2048
	ds_read_b128 v[188:191], v143 offset:3072
	ds_read_b128 v[192:195], v143 offset:4096
	ds_read_b128 v[196:199], v143 offset:5120
	ds_read_b128 v[200:203], v143 offset:6144
	ds_read_b128 v[204:207], v143 offset:7168
	global_load_lds_dwordx4 v[140:141], off
	v_lshl_add_u64 v[140:141], s[12:13], 0, v[138:139]
	s_add_i32 m0, s23, 0xe000
	s_nop 0
	global_load_lds_dwordx4 v[140:141], off
	s_waitcnt lgkmcnt(8)
	s_barrier
	s_waitcnt lgkmcnt(0)
	s_setprio 1
	s_waitcnt lgkmcnt(0)
	v_mfma_f32_16x16x32_bf16 v[130:133], v[144:147], v[170:173], v[130:133]
	v_mfma_f32_16x16x32_bf16 v[126:129], v[162:165], v[170:173], v[126:129]
	v_mfma_f32_16x16x32_bf16 v[114:117], v[144:147], v[178:181], v[114:117]
	v_mfma_f32_16x16x32_bf16 v[110:113], v[162:165], v[178:181], v[110:113]
	v_mfma_f32_16x16x32_bf16 v[98:101], v[144:147], v[192:195], v[98:101]
	v_mfma_f32_16x16x32_bf16 v[94:97], v[162:165], v[192:195], v[94:97]
	v_mfma_f32_16x16x32_bf16 v[82:85], v[144:147], v[200:203], v[82:85]
	v_mfma_f32_16x16x32_bf16 v[78:81], v[162:165], v[200:203], v[78:81]
	v_mfma_f32_16x16x32_bf16 v[130:133], v[148:151], v[174:177], v[130:133]
	v_mfma_f32_16x16x32_bf16 v[126:129], v[166:169], v[174:177], v[126:129]
	v_mfma_f32_16x16x32_bf16 v[114:117], v[148:151], v[188:191], v[114:117]
	v_mfma_f32_16x16x32_bf16 v[110:113], v[166:169], v[188:191], v[110:113]
	v_mfma_f32_16x16x32_bf16 v[98:101], v[148:151], v[196:199], v[98:101]
	v_mfma_f32_16x16x32_bf16 v[94:97], v[166:169], v[196:199], v[94:97]
	v_mfma_f32_16x16x32_bf16 v[82:85], v[148:151], v[204:207], v[82:85]
	v_mfma_f32_16x16x32_bf16 v[78:81], v[166:169], v[204:207], v[78:81]
	s_setprio 0
	s_barrier
	s_add_i32 s40, 0, 0x14000
	v_add_u32_e32 v140, s40, v142
	s_add_i32 s37, s37, s21
	ds_read_b128 v[208:211], v140
	ds_read_b128 v[212:215], v140 offset:1024
	ds_read_b128 v[216:219], v140 offset:2048
	ds_read_b128 v[220:223], v140 offset:3072
	v_lshl_add_u64 v[140:141], s[14:15], 0, v[134:135]
	s_mov_b32 m0, s37
	v_lshl_add_u64 v[154:155], s[14:15], 0, v[18:19]
	global_load_lds_dwordx4 v[140:141], off
	s_add_i32 m0, s37, 0x2000
	s_nop 0
	global_load_lds_dwordx4 v[154:155], off
	s_barrier
	s_waitcnt lgkmcnt(0)
	s_setprio 1
	s_waitcnt lgkmcnt(0)
	v_mfma_f32_16x16x32_bf16 v[122:125], v[208:211], v[170:173], v[122:125]
	v_mfma_f32_16x16x32_bf16 v[118:121], v[216:219], v[170:173], v[118:121]
	v_mfma_f32_16x16x32_bf16 v[106:109], v[208:211], v[178:181], v[106:109]
	v_mfma_f32_16x16x32_bf16 v[102:105], v[216:219], v[178:181], v[102:105]
	v_mfma_f32_16x16x32_bf16 v[90:93], v[208:211], v[192:195], v[90:93]
	v_mfma_f32_16x16x32_bf16 v[86:89], v[216:219], v[192:195], v[86:89]
	v_mfma_f32_16x16x32_bf16 v[74:77], v[208:211], v[200:203], v[74:77]
	v_mfma_f32_16x16x32_bf16 v[70:73], v[216:219], v[200:203], v[70:73]
	v_mfma_f32_16x16x32_bf16 v[122:125], v[212:215], v[174:177], v[122:125]
	v_mfma_f32_16x16x32_bf16 v[118:121], v[220:223], v[174:177], v[118:121]
	v_mfma_f32_16x16x32_bf16 v[106:109], v[212:215], v[188:191], v[106:109]
	v_mfma_f32_16x16x32_bf16 v[102:105], v[220:223], v[188:191], v[102:105]
	v_mfma_f32_16x16x32_bf16 v[90:93], v[212:215], v[196:199], v[90:93]
	v_mfma_f32_16x16x32_bf16 v[86:89], v[220:223], v[196:199], v[86:89]
	v_mfma_f32_16x16x32_bf16 v[74:77], v[212:215], v[204:207], v[74:77]
	v_mfma_f32_16x16x32_bf16 v[70:73], v[220:223], v[204:207], v[70:73]
	s_setprio 0
	s_mov_b32 m0, s23
	v_lshl_add_u64 v[156:157], s[16:17], 0, v[134:135]
	s_barrier
	ds_read_b128 v[170:173], v143 offset:16384
	ds_read_b128 v[174:177], v143 offset:17408
	ds_read_b128 v[178:181], v143 offset:18432
	ds_read_b128 v[188:191], v143 offset:19456
	ds_read_b128 v[192:195], v143 offset:20480
	ds_read_b128 v[196:199], v143 offset:21504
	ds_read_b128 v[200:203], v143 offset:22528
	ds_read_b128 v[204:207], v143 offset:23552
	global_load_lds_dwordx4 v[156:157], off
	v_lshl_add_u64 v[186:187], s[16:17], 0, v[18:19]
	s_mov_b32 m0, s24
	s_nop 0
	global_load_lds_dwordx4 v[186:187], off
	s_barrier
	s_waitcnt lgkmcnt(0)
	s_setprio 1
	s_waitcnt lgkmcnt(0)
	v_mfma_f32_16x16x32_bf16 v[66:69], v[144:147], v[170:173], v[66:69]
	v_mfma_f32_16x16x32_bf16 v[62:65], v[162:165], v[170:173], v[62:65]
	v_mfma_f32_16x16x32_bf16 v[50:53], v[144:147], v[178:181], v[50:53]
	v_mfma_f32_16x16x32_bf16 v[46:49], v[162:165], v[178:181], v[46:49]
	v_mfma_f32_16x16x32_bf16 v[34:37], v[144:147], v[192:195], v[34:37]
	v_mfma_f32_16x16x32_bf16 v[30:33], v[162:165], v[192:195], v[30:33]
	v_mfma_f32_16x16x32_bf16 v[12:15], v[144:147], v[200:203], v[12:15]
	v_mfma_f32_16x16x32_bf16 v[8:11], v[162:165], v[200:203], v[8:11]
	v_mfma_f32_16x16x32_bf16 v[66:69], v[148:151], v[174:177], v[66:69]
	v_mfma_f32_16x16x32_bf16 v[62:65], v[166:169], v[174:177], v[62:65]
	v_mfma_f32_16x16x32_bf16 v[50:53], v[148:151], v[188:191], v[50:53]
	v_mfma_f32_16x16x32_bf16 v[46:49], v[166:169], v[188:191], v[46:49]
	v_mfma_f32_16x16x32_bf16 v[34:37], v[148:151], v[196:199], v[34:37]
	v_mfma_f32_16x16x32_bf16 v[30:33], v[166:169], v[196:199], v[30:33]
	v_mfma_f32_16x16x32_bf16 v[12:15], v[148:151], v[204:207], v[12:15]
	v_mfma_f32_16x16x32_bf16 v[8:11], v[166:169], v[204:207], v[8:11]
	s_setprio 0
	s_barrier
; #define PG8_STAGE(bufoff, gbase, voff) do { _Pragma("unroll") for (int _i = 0; _i < 2; ++_i) \
;         __builtin_amdgcn_global_load_lds((const unsigned*)((const char*)(gbase) + (voff)[_i]), (PG8_LAS unsigned*)(lds + (bufoff) + ldsw + _i * 8192), 16, 0, 0); } while (0)
; #define PG8_LDA(dst, b, h) do { _Pragma("unroll") for (int m = 0; m < 4; ++m) _Pragma("unroll") for (int k = 0; k < 2; ++k) dst[m][k] = *(const PG8_LAS bf16x8*)(lds + PG8_SA(b, h) + aoff + m * 2048 + k * 1024); } while (0)
; #define PG8_LDB(dst, b, h) do { _Pragma("unroll") for (int n = 0; n < 2; ++n) _Pragma("unroll") for (int k = 0; k < 2; ++k) dst[n][k] = *(const PG8_LAS bf16x8*)(lds + PG8_SB(b, h) + boff + n * 2048 + k * 1024); } while (0)
; #define PG8_MMA(ai, bj, At, Bt) do { __builtin_amdgcn_s_setprio(1); _Pragma("unroll") for (int m = 0; m < 4; ++m) _Pragma("unroll") for (int n = 0; n < 2; ++n) _Pragma("unroll") for (int k = 0; k < 2; ++k) \
;         acc[ai][bj][m][n] = __builtin_amdgcn_mfma_f32_16x16x32_bf16(Bt[n][k], At[m][k], acc[ai][bj][m][n], 0, 0, 0); __builtin_amdgcn_s_setprio(0); } while (0)
; #define PG8_WAIT_V(n) asm volatile("s_waitcnt vmcnt(" #n ")" ::: "memory")
; #define PG8_WAIT_L(n) asm volatile("s_waitcnt lgkmcnt(" #n ")" ::: "memory")
; #define PG8_BAR __builtin_amdgcn_s_barrier()
; #define PG8_SCHED __builtin_amdgcn_sched_barrier(0)
; template <class Epi, class Sched>
; __device__ __forceinline__ void gemm_phase(PG8_LAS unsigned char* lds, const Gemm g, const Sched& S, const Epi& E) {
;     ...
;             PG8_STAGE(PG8_SB(0, 1), b2 + hstep, voffB);
;             PG8_WAIT_V(6); PG8_BAR; PG8_MMA(1, 1, At, B1); PG8_BAR;
;             PG8_LDB(B0, 1, 0); PG8_SCHED; PG8_LDA(At, 1, 0); PG8_STAGE(PG8_SA(0, 1), a2 + hstep, voffA);
;             PG8_WAIT_L(8); PG8_BAR; PG8_WAIT_L(0); PG8_MMA(0, 0, At, B0); PG8_BAR; PG8_SCHED;
;             PG8_LDB(B1, 1, 1); PG8_STAGE(PG8_SB(1, 0), b3, voffB);
;             PG8_BAR; PG8_WAIT_L(0); PG8_MMA(0, 1, At, B1); PG8_BAR;
;             PG8_LDA(At, 1, 1); PG8_STAGE(PG8_SA(1, 0), a3, voffA);
	s_add_u32 s38, s14, 0x40000
	s_addc_u32 s39, s15, 0
	s_add_i32 s37, s40, s21
	v_lshl_add_u64 v[144:145], s[38:39], 0, v[134:135]
	s_mov_b32 m0, s37
	s_nop 0
	global_load_lds_dwordx4 v[144:145], off
	v_lshl_add_u64 v[144:145], s[38:39], 0, v[18:19]
	s_add_i32 m0, s37, 0x2000
	s_nop 0
	global_load_lds_dwordx4 v[144:145], off
	s_waitcnt vmcnt(6)
	s_barrier
	s_setprio 1
	v_mfma_f32_16x16x32_bf16 v[58:61], v[208:211], v[170:173], v[58:61]
	v_mfma_f32_16x16x32_bf16 v[54:57], v[216:219], v[170:173], v[54:57]
	v_mfma_f32_16x16x32_bf16 v[42:45], v[208:211], v[178:181], v[42:45]
	v_mfma_f32_16x16x32_bf16 v[38:41], v[216:219], v[178:181], v[38:41]
	v_mfma_f32_16x16x32_bf16 v[26:29], v[208:211], v[192:195], v[26:29]
	v_mfma_f32_16x16x32_bf16 v[22:25], v[216:219], v[192:195], v[22:25]
	v_mfma_f32_16x16x32_bf16 v[4:7], v[208:211], v[200:203], v[4:7]
	v_mfma_f32_16x16x32_bf16 v[0:3], v[216:219], v[200:203], v[0:3]
	v_mfma_f32_16x16x32_bf16 v[58:61], v[212:215], v[174:177], v[58:61]
	v_mfma_f32_16x16x32_bf16 v[54:57], v[220:223], v[174:177], v[54:57]
	v_mfma_f32_16x16x32_bf16 v[42:45], v[212:215], v[188:191], v[42:45]
	v_mfma_f32_16x16x32_bf16 v[38:41], v[220:223], v[188:191], v[38:41]
	v_mfma_f32_16x16x32_bf16 v[26:29], v[212:215], v[196:199], v[26:29]
	v_mfma_f32_16x16x32_bf16 v[22:25], v[220:223], v[196:199], v[22:25]
	v_mfma_f32_16x16x32_bf16 v[4:7], v[212:215], v[204:207], v[4:7]
	v_mfma_f32_16x16x32_bf16 v[0:3], v[220:223], v[204:207], v[0:3]
	s_setprio 0
	s_add_i32 s37, 0, 0x18000
	v_add_u32_e32 v166, s37, v142
	s_barrier
	ds_read_b128 v[144:147], v166
	ds_read_b128 v[148:151], v166 offset:1024
	ds_read_b128 v[162:165], v166 offset:2048
	ds_read_b128 v[166:169], v166 offset:3072
	s_add_u32 s16, s16, 0x40000
	s_addc_u32 s17, s17, 0
	s_mov_b32 m0, s25
	v_lshl_add_u64 v[208:209], s[16:17], 0, v[134:135]
	ds_read_b128 v[170:173], v143 offset:32768
	ds_read_b128 v[174:177], v143 offset:33792
	ds_read_b128 v[178:181], v143 offset:34816
	ds_read_b128 v[188:191], v143 offset:35840
	ds_read_b128 v[192:195], v143 offset:36864
	ds_read_b128 v[196:199], v143 offset:37888
	ds_read_b128 v[200:203], v143 offset:38912
	ds_read_b128 v[204:207], v143 offset:39936
	global_load_lds_dwordx4 v[208:209], off
	v_lshl_add_u64 v[208:209], s[16:17], 0, v[18:19]
	s_mov_b32 m0, s26
	s_nop 0
	global_load_lds_dwordx4 v[208:209], off
	s_waitcnt lgkmcnt(8)
	s_barrier
	s_waitcnt lgkmcnt(0)
	s_setprio 1
	s_waitcnt lgkmcnt(0)
	v_mfma_f32_16x16x32_bf16 v[130:133], v[144:147], v[170:173], v[130:133]
	v_mfma_f32_16x16x32_bf16 v[126:129], v[162:165], v[170:173], v[126:129]
	v_mfma_f32_16x16x32_bf16 v[114:117], v[144:147], v[178:181], v[114:117]
	v_mfma_f32_16x16x32_bf16 v[110:113], v[162:165], v[178:181], v[110:113]
	v_mfma_f32_16x16x32_bf16 v[98:101], v[144:147], v[192:195], v[98:101]
	v_mfma_f32_16x16x32_bf16 v[94:97], v[162:165], v[192:195], v[94:97]
	v_mfma_f32_16x16x32_bf16 v[82:85], v[144:147], v[200:203], v[82:85]
	v_mfma_f32_16x16x32_bf16 v[78:81], v[162:165], v[200:203], v[78:81]
	v_mfma_f32_16x16x32_bf16 v[130:133], v[148:151], v[174:177], v[130:133]
	v_mfma_f32_16x16x32_bf16 v[126:129], v[166:169], v[174:177], v[126:129]
	v_mfma_f32_16x16x32_bf16 v[114:117], v[148:151], v[188:191], v[114:117]
	v_mfma_f32_16x16x32_bf16 v[110:113], v[166:169], v[188:191], v[110:113]
	v_mfma_f32_16x16x32_bf16 v[98:101], v[148:151], v[196:199], v[98:101]
	v_mfma_f32_16x16x32_bf16 v[94:97], v[166:169], v[196:199], v[94:97]
	v_mfma_f32_16x16x32_bf16 v[82:85], v[148:151], v[204:207], v[82:85]
	v_mfma_f32_16x16x32_bf16 v[78:81], v[166:169], v[204:207], v[78:81]
	s_setprio 0
	s_barrier
	s_add_i32 s16, 0, 0x1c000
	s_add_i32 s17, s37, s21
	v_add_u32_e32 v220, s16, v142
	v_lshl_add_u64 v[140:141], v[140:141], 0, s[42:43]
	s_mov_b32 m0, s17
	ds_read_b128 v[208:211], v220
	ds_read_b128 v[212:215], v220 offset:1024
	ds_read_b128 v[216:219], v220 offset:2048
	ds_read_b128 v[220:223], v220 offset:3072
	global_load_lds_dwordx4 v[140:141], off
	v_lshl_add_u64 v[140:141], v[154:155], 0, s[42:43]
	s_add_i32 m0, s17, 0x2000
	s_nop 0
	global_load_lds_dwordx4 v[140:141], off
	s_barrier
	s_waitcnt lgkmcnt(0)
	s_setprio 1
	s_waitcnt lgkmcnt(0)
	v_mfma_f32_16x16x32_bf16 v[122:125], v[208:211], v[170:173], v[122:125]
	v_mfma_f32_16x16x32_bf16 v[118:121], v[216:219], v[170:173], v[118:121]
	v_mfma_f32_16x16x32_bf16 v[106:109], v[208:211], v[178:181], v[106:109]
	v_mfma_f32_16x16x32_bf16 v[102:105], v[216:219], v[178:181], v[102:105]
	v_mfma_f32_16x16x32_bf16 v[90:93], v[208:211], v[192:195], v[90:93]
	v_mfma_f32_16x16x32_bf16 v[86:89], v[216:219], v[192:195], v[86:89]
	v_mfma_f32_16x16x32_bf16 v[74:77], v[208:211], v[200:203], v[74:77]
	v_mfma_f32_16x16x32_bf16 v[70:73], v[216:219], v[200:203], v[70:73]
	v_mfma_f32_16x16x32_bf16 v[122:125], v[212:215], v[174:177], v[122:125]
	v_mfma_f32_16x16x32_bf16 v[118:121], v[220:223], v[174:177], v[118:121]
	v_mfma_f32_16x16x32_bf16 v[106:109], v[212:215], v[188:191], v[106:109]
	v_mfma_f32_16x16x32_bf16 v[102:105], v[220:223], v[188:191], v[102:105]
	v_mfma_f32_16x16x32_bf16 v[90:93], v[212:215], v[196:199], v[90:93]
	v_mfma_f32_16x16x32_bf16 v[86:89], v[220:223], v[196:199], v[86:89]
	v_mfma_f32_16x16x32_bf16 v[74:77], v[212:215], v[204:207], v[74:77]
	v_mfma_f32_16x16x32_bf16 v[70:73], v[220:223], v[204:207], v[70:73]
	s_setprio 0
	s_mov_b32 m0, s27
	v_lshl_add_u64 v[140:141], v[156:157], 0, s[42:43]
	s_barrier
	ds_read_b128 v[170:173], v143 offset:49152
	ds_read_b128 v[174:177], v143 offset:50176
	ds_read_b128 v[178:181], v143 offset:51200
	ds_read_b128 v[188:191], v143 offset:52224
	ds_read_b128 v[192:195], v143 offset:53248
	ds_read_b128 v[196:199], v143 offset:54272
	ds_read_b128 v[200:203], v143 offset:55296
	ds_read_b128 v[204:207], v143 offset:56320
	global_load_lds_dwordx4 v[140:141], off
	v_lshl_add_u64 v[140:141], v[186:187], 0, s[42:43]
	s_mov_b32 m0, s28
	s_nop 0
	global_load_lds_dwordx4 v[140:141], off
	s_barrier
; DI bf16x4 pack4(float a, float b, float c, float d) { u32x2v u; u.x = pk2(a, b); u.y = pk2(c, d); return __builtin_bit_cast(bf16x4, u); }
; #define PG8_STAGE(bufoff, gbase, voff) do { _Pragma("unroll") for (int _i = 0; _i < 2; ++_i) \
;         __builtin_amdgcn_global_load_lds((const unsigned*)((const char*)(gbase) + (voff)[_i]), (PG8_LAS unsigned*)(lds + (bufoff) + ldsw + _i * 8192), 16, 0, 0); } while (0)
; #define PG8_WAIT_V(n) asm volatile("s_waitcnt vmcnt(" #n ")" ::: "memory")
; #define PG8_WAIT_L(n) asm volatile("s_waitcnt lgkmcnt(" #n ")" ::: "memory")
; template <class Epi, class Sched>
; __device__ __forceinline__ void gemm_phase(PG8_LAS unsigned char* lds, const Gemm g, const Sched& S, const Epi& E) {
;     ...
;             PG8_LDA(At, 1, 1); PG8_STAGE(PG8_SA(1, 0), a3, voffA);
;             PG8_BAR; PG8_WAIT_L(0); PG8_MMA(1, 0, At, B0); PG8_BAR; PG8_SCHED;
;             PG8_STAGE(PG8_SB(1, 1), b3 + hstep, voffB);
;             PG8_WAIT_V(6); PG8_BAR; PG8_MMA(1, 1, At, B1); PG8_BAR;
;         }
;         if constexpr (!Epi::AFTER_DRAIN) { E(acc, cur, wr, wc, fr, fq); S.done(cur); }
;         if (!has_next) break;
;   DI void operator()(const f32x4 (&acc)[2][2][4][2], const pg8::Unit& u, int wr, int wc, int fr, int fq) const {
;     bf16_t* MERGED = (reinterpret_cast<bf16_t*>(p.ws + OFF_GA));
; #pragma unroll
;     for (int ai = 0; ai < 2; ++ai)
; #pragma unroll
;       for (int m = 0; m < 4; ++m) {
;         const int row = u.pm * 256 + 128 * ai + 64 * wr + 16 * m + fr;
; #pragma unroll
;         for (int bj = 0; bj < 2; ++bj)
; #pragma unroll
;           for (int n = 0; n < 2; ++n) {
;             const size_t idx = (size_t)row * 1024 + u.pn * 256 + 128 * bj + 32 * wc + 16 * n + 4 * fq;
;             const f32x4 a = acc[ai][bj][m][n];
;             if (MODE == 0) {
;               const unsigned g = *reinterpret_cast<const unsigned*>(reinterpret_cast<const unsigned char*>(p.ws + OFF_RB) + idx);
;               const float k = 1.f / 255.f;
;               st4(MERGED + idx, pack4((float)(g & 255u) * k * a[0], (float)((g >> 8) & 255u) * k * a[1], (float)((g >> 16) & 255u) * k * a[2], (float)(g >> 24) * k * a[3]));
;             } else {
;               f32x4 x = *reinterpret_cast<const f32x4*>(p.out + idx);
;               x = x * ALPHA + a;
;               *reinterpret_cast<f32x4*>(p.out + idx) = x;
;             }
	s_waitcnt lgkmcnt(0)
	s_setprio 1
	s_waitcnt lgkmcnt(0)
	v_mfma_f32_16x16x32_bf16 v[66:69], v[144:147], v[170:173], v[66:69]
	v_mfma_f32_16x16x32_bf16 v[62:65], v[162:165], v[170:173], v[62:65]
	v_mfma_f32_16x16x32_bf16 v[50:53], v[144:147], v[178:181], v[50:53]
	v_mfma_f32_16x16x32_bf16 v[46:49], v[162:165], v[178:181], v[46:49]
	v_mfma_f32_16x16x32_bf16 v[34:37], v[144:147], v[192:195], v[34:37]
	v_mfma_f32_16x16x32_bf16 v[30:33], v[162:165], v[192:195], v[30:33]
	v_mfma_f32_16x16x32_bf16 v[12:15], v[144:147], v[200:203], v[12:15]
	v_mfma_f32_16x16x32_bf16 v[8:11], v[162:165], v[200:203], v[8:11]
	v_mfma_f32_16x16x32_bf16 v[66:69], v[148:151], v[174:177], v[66:69]
	v_mfma_f32_16x16x32_bf16 v[62:65], v[166:169], v[174:177], v[62:65]
	v_mfma_f32_16x16x32_bf16 v[50:53], v[148:151], v[188:191], v[50:53]
	v_mfma_f32_16x16x32_bf16 v[46:49], v[166:169], v[188:191], v[46:49]
	v_mfma_f32_16x16x32_bf16 v[34:37], v[148:151], v[196:199], v[34:37]
	v_mfma_f32_16x16x32_bf16 v[30:33], v[166:169], v[196:199], v[30:33]
	v_mfma_f32_16x16x32_bf16 v[12:15], v[148:151], v[204:207], v[12:15]
	v_mfma_f32_16x16x32_bf16 v[8:11], v[166:169], v[204:207], v[8:11]
	s_setprio 0
	s_barrier
	s_add_u32 s14, s14, 0x40080
	s_addc_u32 s15, s15, 0
	s_add_i32 s16, s16, s21
	v_lshl_add_u64 v[140:141], s[14:15], 0, v[134:135]
	s_mov_b32 m0, s16
	s_nop 0
	global_load_lds_dwordx4 v[140:141], off
	v_lshl_add_u64 v[140:141], s[14:15], 0, v[18:19]
	s_add_i32 m0, s16, 0x2000
	s_nop 0
	global_load_lds_dwordx4 v[140:141], off
	s_waitcnt vmcnt(6)
	s_barrier
	s_setprio 1
	v_mfma_f32_16x16x32_bf16 v[58:61], v[208:211], v[170:173], v[58:61]
	v_mfma_f32_16x16x32_bf16 v[54:57], v[216:219], v[170:173], v[54:57]
	v_mfma_f32_16x16x32_bf16 v[42:45], v[208:211], v[178:181], v[42:45]
	v_mfma_f32_16x16x32_bf16 v[38:41], v[216:219], v[178:181], v[38:41]
	v_mfma_f32_16x16x32_bf16 v[26:29], v[208:211], v[192:195], v[26:29]
	v_mfma_f32_16x16x32_bf16 v[22:25], v[216:219], v[192:195], v[22:25]
	v_mfma_f32_16x16x32_bf16 v[4:7], v[208:211], v[200:203], v[4:7]
	v_mfma_f32_16x16x32_bf16 v[0:3], v[216:219], v[200:203], v[0:3]
	v_mfma_f32_16x16x32_bf16 v[58:61], v[212:215], v[174:177], v[58:61]
	v_mfma_f32_16x16x32_bf16 v[54:57], v[220:223], v[174:177], v[54:57]
	v_mfma_f32_16x16x32_bf16 v[42:45], v[212:215], v[188:191], v[42:45]
	v_mfma_f32_16x16x32_bf16 v[38:41], v[220:223], v[188:191], v[38:41]
	v_mfma_f32_16x16x32_bf16 v[26:29], v[212:215], v[196:199], v[26:29]
	v_mfma_f32_16x16x32_bf16 v[22:25], v[220:223], v[196:199], v[22:25]
	v_mfma_f32_16x16x32_bf16 v[4:7], v[212:215], v[204:207], v[4:7]
	v_mfma_f32_16x16x32_bf16 v[0:3], v[220:223], v[204:207], v[0:3]
	s_setprio 0
	s_add_i32 s36, s36, 2
	s_add_u32 s12, s12, 0x100
	s_addc_u32 s13, s13, 0
	s_add_u32 s34, s34, 0x100
	s_addc_u32 s35, s35, 0
	s_cmp_gt_u32 s36, 13
	s_barrier
	s_cbranch_scc0 .LBB0_2754
	v_readlane_b32 s12, v251, 8
	s_cmp_eq_u32 s12, 0
	s_cbranch_scc1 .Llz_plain
	v_lshl_add_u32 v140, s10, 8, v21
	s_lshl_b32 s10, s11, 10
	v_readlane_b32 s14, v249, 4
	v_readlane_b32 s15, v249, 5
	v_readlane_b32 s13, v251, 6
	s_mov_b32 s16, 0x3fd744fd
	v_and_b32_e32 v147, 63, v153
	v_and_b32_e32 v148, 15, v153
	v_lshrrev_b32_e32 v149, 3, v147
	s_add_i32 s10, s10, s13
	s_add_i32 s12, s12, -1
	s_lshl_b32 s12, s12, 12
	v_sub_u32_e32 v140, v140, v148
	v_add_u32_e32 v140, v140, v149
	v_and_b32_e32 v146, 7, v153
	v_lshlrev_b32_e32 v141, 3, v140
	v_lshl_add_u32 v146, v146, 4, s10
	v_lshl_add_u32 v140, v140, 12, v146
	v_lshrrev_b32_e32 v144, 6, v153
	v_lshlrev_b32_e32 v144, 11, v144
	v_add_u32_e32 v144, 0x20000, v144
	v_lshl_add_u32 v145, v149, 6, v144
	v_lshl_add_u32 v144, v148, 6, v144
	v_bfe_u32 v148, v153, 4, 2
	v_lshl_add_u32 v144, v148, 4, v144
	v_bfe_u32 v148, v153, 2, 1
	v_lshl_add_u32 v145, v148, 10, v145
	v_and_b32_e32 v148, 3, v153
	v_lshl_add_u32 v145, v148, 4, v145
	v_readlane_b32 s72, v249, 38
	v_readlane_b32 s73, v249, 39
	v_readlane_b32 s74, v249, 40
	v_readlane_b32 s75, v249, 41
	v_readlane_b32 s76, v249, 0
	v_readlane_b32 s77, v249, 1
	s_add_u32 s72, s72, s12
	s_addc_u32 s73, s73, 0
	s_add_u32 s74, s74, s12
	s_addc_u32 s75, s75, 0
	s_add_u32 s76, s76, 0x2b234000
	s_addc_u32 s77, s77, 0
	s_add_u32 s56, s14, 0x0
	s_addc_u32 s57, s15, 0
	s_add_u32 s78, s14, 0x8000
	s_addc_u32 s79, s15, 0
	s_add_u32 s58, s14, 0x10000
	s_addc_u32 s59, s15, 0
	s_add_u32 s80, s14, 0x18000
	s_addc_u32 s81, s15, 0
	s_add_u32 s60, s14, 0x20000
	s_addc_u32 s61, s15, 0
	s_add_u32 s82, s14, 0x28000
	s_addc_u32 s83, s15, 0
	s_add_u32 s62, s14, 0x30000
	s_addc_u32 s63, s15, 0
	s_add_u32 s84, s14, 0x38000
	s_addc_u32 s85, s15, 0
	s_add_u32 s64, s14, 0x80000
	s_addc_u32 s65, s15, 0
	s_add_u32 s86, s14, 0x88000
	s_addc_u32 s87, s15, 0
	s_add_u32 s66, s14, 0x90000
	s_addc_u32 s67, s15, 0
	s_add_u32 s88, s14, 0x98000
	s_addc_u32 s89, s15, 0
	s_add_u32 s68, s14, 0xa0000
	s_addc_u32 s69, s15, 0
	s_add_u32 s90, s14, 0xa8000
	s_addc_u32 s91, s15, 0
	s_add_u32 s70, s14, 0xb0000
	s_addc_u32 s71, s15, 0
	s_add_u32 s92, s14, 0xb8000
	s_addc_u32 s93, s15, 0
	s_nop 1
	global_load_dwordx2 v[174:175], v141, s[76:77] offset:0
	global_load_dwordx2 v[176:177], v141, s[76:77] offset:64
	global_load_dwordx2 v[178:179], v141, s[76:77] offset:128
	global_load_dwordx2 v[180:181], v141, s[76:77] offset:192
	global_load_dwordx4 v[154:157], v146, s[72:73]
	global_load_dwordx4 v[162:165], v146, s[74:75]
	global_load_dwordx4 v[166:169], v146, s[72:73] offset:512
	global_load_dwordx4 v[170:173], v146, s[74:75] offset:512
	global_load_dwordx4 v[204:207], v140, s[56:57]
	global_load_dwordx4 v[208:211], v140, s[78:79]
	global_load_dwordx4 v[212:215], v140, s[56:57] offset:512
	global_load_dwordx4 v[216:219], v140, s[78:79] offset:512
	global_load_dwordx4 v[220:223], v140, s[58:59]
	global_load_dwordx4 v[224:227], v140, s[80:81]
	global_load_dwordx4 v[228:231], v140, s[58:59] offset:512
	global_load_dwordx4 v[232:235], v140, s[80:81] offset:512
	global_load_dwordx4 v[236:239], v140, s[60:61]
	global_load_dwordx4 v[240:243], v140, s[82:83]
	global_load_dwordx4 v[244:247], v140, s[60:61] offset:512
	ds_write_b128 v144, v[130:133]
	ds_write_b128 v144, v[126:129] offset:1024
	ds_read_b128 v[186:189], v145
	ds_read_b128 v[190:193], v145 offset:512
	ds_write_b128 v144, v[122:125]
	ds_write_b128 v144, v[118:121] offset:1024
	ds_read_b128 v[194:197], v145
	ds_read_b128 v[198:201], v145 offset:512
	s_waitcnt lgkmcnt(4)
; DI bf16x4 pack4(float a, float b, float c, float d) { u32x2v u; u.x = pk2(a, b); u.y = pk2(c, d); return __builtin_bit_cast(bf16x4, u); }
; DI void ln_row_wave(const float* src, const float* g, const float* b, float* d32, bf16_t* db, int lane) {
;     ...
;   for (int i = 0; i < 4; ++i) {
;     float4 gg = reinterpret_cast<const float4*>(g)[lane + 64 * i], bb = reinterpret_cast<const float4*>(b)[lane + 64 * i];
;     float4 o;
;     o.x = (v[i].x - mu) * rstd * gg.x + bb.x; o.y = (v[i].y - mu) * rstd * gg.y + bb.y;
;     o.z = (v[i].z - mu) * rstd * gg.z + bb.z; o.w = (v[i].w - mu) * rstd * gg.w + bb.w;
;   DI void operator()(const f32x4 (&acc)[2][2][4][2], const pg8::Unit& u, int wr, int wc, int fr, int fq) const {
;     bf16_t* MERGED = (reinterpret_cast<bf16_t*>(p.ws + OFF_GA));
; #pragma unroll
;     for (int ai = 0; ai < 2; ++ai)
; #pragma unroll
;       for (int m = 0; m < 4; ++m) {
;         const int row = u.pm * 256 + 128 * ai + 64 * wr + 16 * m + fr;
; #pragma unroll
;         for (int bj = 0; bj < 2; ++bj)
; #pragma unroll
;           for (int n = 0; n < 2; ++n) {
;             const size_t idx = (size_t)row * 1024 + u.pn * 256 + 128 * bj + 32 * wc + 16 * n + 4 * fq;
;             const f32x4 a = acc[ai][bj][m][n];
;             if (MODE == 0) {
;               const unsigned g = *reinterpret_cast<const unsigned*>(reinterpret_cast<const unsigned char*>(p.ws + OFF_RB) + idx);
;               const float k = 1.f / 255.f;
;               st4(MERGED + idx, pack4((float)(g & 255u) * k * a[0], (float)((g >> 8) & 255u) * k * a[1], (float)((g >> 16) & 255u) * k * a[2], (float)(g >> 24) * k * a[3]));
;             } else {
;               f32x4 x = *reinterpret_cast<const f32x4*>(p.out + idx);
;               x = x * ALPHA + a;
;               *reinterpret_cast<f32x4*>(p.out + idx) = x;
;             }
	s_waitcnt vmcnt(10)
	v_pk_add_f32 v[204:205], v[204:205], v[174:175] op_sel_hi:[1,0] neg_lo:[0,1] neg_hi:[0,1]
	v_pk_add_f32 v[206:207], v[206:207], v[174:175] op_sel_hi:[1,0] neg_lo:[0,1] neg_hi:[0,1]
	v_pk_mul_f32 v[204:205], v[204:205], v[174:175] op_sel:[0,1] op_sel_hi:[1,1]
	v_pk_mul_f32 v[206:207], v[206:207], v[174:175] op_sel:[0,1] op_sel_hi:[1,1]
	v_pk_fma_f32 v[204:205], v[204:205], v[154:155], v[162:163]
	v_pk_fma_f32 v[206:207], v[206:207], v[156:157], v[164:165]
	v_pk_fma_f32 v[186:187], v[204:205], s[16:17], v[186:187] op_sel_hi:[1,0,1]
	v_pk_fma_f32 v[188:189], v[206:207], s[16:17], v[188:189] op_sel_hi:[1,0,1]
	global_store_dwordx4 v140, v[186:189], s[56:57]
	global_load_dwordx4 v[204:207], v140, s[82:83] offset:512
	s_waitcnt vmcnt(11)
	v_pk_add_f32 v[208:209], v[208:209], v[176:177] op_sel_hi:[1,0] neg_lo:[0,1] neg_hi:[0,1]
	v_pk_add_f32 v[210:211], v[210:211], v[176:177] op_sel_hi:[1,0] neg_lo:[0,1] neg_hi:[0,1]
	v_pk_mul_f32 v[208:209], v[208:209], v[176:177] op_sel:[0,1] op_sel_hi:[1,1]
	v_pk_mul_f32 v[210:211], v[210:211], v[176:177] op_sel:[0,1] op_sel_hi:[1,1]
	v_pk_fma_f32 v[208:209], v[208:209], v[154:155], v[162:163]
	v_pk_fma_f32 v[210:211], v[210:211], v[156:157], v[164:165]
	v_pk_fma_f32 v[190:191], v[208:209], s[16:17], v[190:191] op_sel_hi:[1,0,1]
	v_pk_fma_f32 v[192:193], v[210:211], s[16:17], v[192:193] op_sel_hi:[1,0,1]
	global_store_dwordx4 v140, v[190:193], s[78:79]
	global_load_dwordx4 v[208:211], v140, s[62:63]
	ds_write_b128 v144, v[114:117]
	ds_write_b128 v144, v[110:113] offset:1024
	ds_read_b128 v[186:189], v145
	ds_read_b128 v[190:193], v145 offset:512
	s_waitcnt lgkmcnt(4)
	s_waitcnt vmcnt(12)
	v_pk_add_f32 v[212:213], v[212:213], v[174:175] op_sel_hi:[1,0] neg_lo:[0,1] neg_hi:[0,1]
	v_pk_add_f32 v[214:215], v[214:215], v[174:175] op_sel_hi:[1,0] neg_lo:[0,1] neg_hi:[0,1]
	v_pk_mul_f32 v[212:213], v[212:213], v[174:175] op_sel:[0,1] op_sel_hi:[1,1]
	v_pk_mul_f32 v[214:215], v[214:215], v[174:175] op_sel:[0,1] op_sel_hi:[1,1]
	v_pk_fma_f32 v[212:213], v[212:213], v[166:167], v[170:171]
	v_pk_fma_f32 v[214:215], v[214:215], v[168:169], v[172:173]
	v_pk_fma_f32 v[194:195], v[212:213], s[16:17], v[194:195] op_sel_hi:[1,0,1]
	v_pk_fma_f32 v[196:197], v[214:215], s[16:17], v[196:197] op_sel_hi:[1,0,1]
	global_store_dwordx4 v140, v[194:197], s[56:57] offset:512
	global_load_dwordx4 v[212:215], v140, s[84:85]
	s_waitcnt vmcnt(13)
	v_pk_add_f32 v[216:217], v[216:217], v[176:177] op_sel_hi:[1,0] neg_lo:[0,1] neg_hi:[0,1]
	v_pk_add_f32 v[218:219], v[218:219], v[176:177] op_sel_hi:[1,0] neg_lo:[0,1] neg_hi:[0,1]
	v_pk_mul_f32 v[216:217], v[216:217], v[176:177] op_sel:[0,1] op_sel_hi:[1,1]
	v_pk_mul_f32 v[218:219], v[218:219], v[176:177] op_sel:[0,1] op_sel_hi:[1,1]
	v_pk_fma_f32 v[216:217], v[216:217], v[166:167], v[170:171]
	v_pk_fma_f32 v[218:219], v[218:219], v[168:169], v[172:173]
	v_pk_fma_f32 v[198:199], v[216:217], s[16:17], v[198:199] op_sel_hi:[1,0,1]
	v_pk_fma_f32 v[200:201], v[218:219], s[16:17], v[200:201] op_sel_hi:[1,0,1]
	global_store_dwordx4 v140, v[198:201], s[78:79] offset:512
	global_load_dwordx4 v[216:219], v140, s[62:63] offset:512
	global_load_dwordx2 v[174:175], v141, s[76:77] offset:256
	global_load_dwordx2 v[176:177], v141, s[76:77] offset:320
	ds_write_b128 v144, v[106:109]
	ds_write_b128 v144, v[102:105] offset:1024
	ds_read_b128 v[194:197], v145
	ds_read_b128 v[198:201], v145 offset:512
	s_waitcnt lgkmcnt(4)
	s_waitcnt vmcnt(16)
	v_pk_add_f32 v[220:221], v[220:221], v[178:179] op_sel_hi:[1,0] neg_lo:[0,1] neg_hi:[0,1]
	v_pk_add_f32 v[222:223], v[222:223], v[178:179] op_sel_hi:[1,0] neg_lo:[0,1] neg_hi:[0,1]
	v_pk_mul_f32 v[220:221], v[220:221], v[178:179] op_sel:[0,1] op_sel_hi:[1,1]
	v_pk_mul_f32 v[222:223], v[222:223], v[178:179] op_sel:[0,1] op_sel_hi:[1,1]
	v_pk_fma_f32 v[220:221], v[220:221], v[154:155], v[162:163]
	v_pk_fma_f32 v[222:223], v[222:223], v[156:157], v[164:165]
	v_pk_fma_f32 v[186:187], v[220:221], s[16:17], v[186:187] op_sel_hi:[1,0,1]
	v_pk_fma_f32 v[188:189], v[222:223], s[16:17], v[188:189] op_sel_hi:[1,0,1]
	global_store_dwordx4 v140, v[186:189], s[58:59]
	global_load_dwordx4 v[220:223], v140, s[84:85] offset:512
	s_waitcnt vmcnt(17)
	v_pk_add_f32 v[224:225], v[224:225], v[180:181] op_sel_hi:[1,0] neg_lo:[0,1] neg_hi:[0,1]
	v_pk_add_f32 v[226:227], v[226:227], v[180:181] op_sel_hi:[1,0] neg_lo:[0,1] neg_hi:[0,1]
	v_pk_mul_f32 v[224:225], v[224:225], v[180:181] op_sel:[0,1] op_sel_hi:[1,1]
	v_pk_mul_f32 v[226:227], v[226:227], v[180:181] op_sel:[0,1] op_sel_hi:[1,1]
	v_pk_fma_f32 v[224:225], v[224:225], v[154:155], v[162:163]
	v_pk_fma_f32 v[226:227], v[226:227], v[156:157], v[164:165]
	v_pk_fma_f32 v[190:191], v[224:225], s[16:17], v[190:191] op_sel_hi:[1,0,1]
	v_pk_fma_f32 v[192:193], v[226:227], s[16:17], v[192:193] op_sel_hi:[1,0,1]
	global_store_dwordx4 v140, v[190:193], s[80:81]
	global_load_dwordx4 v[224:227], v140, s[64:65]
	ds_write_b128 v144, v[98:101]
	ds_write_b128 v144, v[94:97] offset:1024
	ds_read_b128 v[186:189], v145
	ds_read_b128 v[190:193], v145 offset:512
	s_waitcnt lgkmcnt(4)
	s_waitcnt vmcnt(18)
	v_pk_add_f32 v[228:229], v[228:229], v[178:179] op_sel_hi:[1,0] neg_lo:[0,1] neg_hi:[0,1]
	v_pk_add_f32 v[230:231], v[230:231], v[178:179] op_sel_hi:[1,0] neg_lo:[0,1] neg_hi:[0,1]
	v_pk_mul_f32 v[228:229], v[228:229], v[178:179] op_sel:[0,1] op_sel_hi:[1,1]
	v_pk_mul_f32 v[230:231], v[230:231], v[178:179] op_sel:[0,1] op_sel_hi:[1,1]
	v_pk_fma_f32 v[228:229], v[228:229], v[166:167], v[170:171]
	v_pk_fma_f32 v[230:231], v[230:231], v[168:169], v[172:173]
	v_pk_fma_f32 v[194:195], v[228:229], s[16:17], v[194:195] op_sel_hi:[1,0,1]
	v_pk_fma_f32 v[196:197], v[230:231], s[16:17], v[196:197] op_sel_hi:[1,0,1]
	global_store_dwordx4 v140, v[194:197], s[58:59] offset:512
	global_load_dwordx4 v[228:231], v140, s[86:87]
	s_waitcnt vmcnt(19)
; DI bf16x4 pack4(float a, float b, float c, float d) { u32x2v u; u.x = pk2(a, b); u.y = pk2(c, d); return __builtin_bit_cast(bf16x4, u); }
; DI void ln_row_wave(const float* src, const float* g, const float* b, float* d32, bf16_t* db, int lane) {
;     ...
;   for (int i = 0; i < 4; ++i) {
;     float4 gg = reinterpret_cast<const float4*>(g)[lane + 64 * i], bb = reinterpret_cast<const float4*>(b)[lane + 64 * i];
;     float4 o;
;     o.x = (v[i].x - mu) * rstd * gg.x + bb.x; o.y = (v[i].y - mu) * rstd * gg.y + bb.y;
;     o.z = (v[i].z - mu) * rstd * gg.z + bb.z; o.w = (v[i].w - mu) * rstd * gg.w + bb.w;
;   DI void operator()(const f32x4 (&acc)[2][2][4][2], const pg8::Unit& u, int wr, int wc, int fr, int fq) const {
;     bf16_t* MERGED = (reinterpret_cast<bf16_t*>(p.ws + OFF_GA));
; #pragma unroll
;     for (int ai = 0; ai < 2; ++ai)
; #pragma unroll
;       for (int m = 0; m < 4; ++m) {
;         const int row = u.pm * 256 + 128 * ai + 64 * wr + 16 * m + fr;
; #pragma unroll
;         for (int bj = 0; bj < 2; ++bj)
; #pragma unroll
;           for (int n = 0; n < 2; ++n) {
;             const size_t idx = (size_t)row * 1024 + u.pn * 256 + 128 * bj + 32 * wc + 16 * n + 4 * fq;
;             const f32x4 a = acc[ai][bj][m][n];
;             if (MODE == 0) {
;               const unsigned g = *reinterpret_cast<const unsigned*>(reinterpret_cast<const unsigned char*>(p.ws + OFF_RB) + idx);
;               const float k = 1.f / 255.f;
;               st4(MERGED + idx, pack4((float)(g & 255u) * k * a[0], (float)((g >> 8) & 255u) * k * a[1], (float)((g >> 16) & 255u) * k * a[2], (float)(g >> 24) * k * a[3]));
;             } else {
;               f32x4 x = *reinterpret_cast<const f32x4*>(p.out + idx);
;               x = x * ALPHA + a;
;               *reinterpret_cast<f32x4*>(p.out + idx) = x;
;             }
	v_pk_add_f32 v[232:233], v[232:233], v[180:181] op_sel_hi:[1,0] neg_lo:[0,1] neg_hi:[0,1]
	v_pk_add_f32 v[234:235], v[234:235], v[180:181] op_sel_hi:[1,0] neg_lo:[0,1] neg_hi:[0,1]
	v_pk_mul_f32 v[232:233], v[232:233], v[180:181] op_sel:[0,1] op_sel_hi:[1,1]
	v_pk_mul_f32 v[234:235], v[234:235], v[180:181] op_sel:[0,1] op_sel_hi:[1,1]
	v_pk_fma_f32 v[232:233], v[232:233], v[166:167], v[170:171]
	v_pk_fma_f32 v[234:235], v[234:235], v[168:169], v[172:173]
	v_pk_fma_f32 v[198:199], v[232:233], s[16:17], v[198:199] op_sel_hi:[1,0,1]
	v_pk_fma_f32 v[200:201], v[234:235], s[16:17], v[200:201] op_sel_hi:[1,0,1]
	global_store_dwordx4 v140, v[198:201], s[80:81] offset:512
	global_load_dwordx4 v[232:235], v140, s[64:65] offset:512
	global_load_dwordx2 v[178:179], v141, s[76:77] offset:384
	global_load_dwordx2 v[180:181], v141, s[76:77] offset:448
	ds_write_b128 v144, v[90:93]
	ds_write_b128 v144, v[86:89] offset:1024
	ds_read_b128 v[194:197], v145
	ds_read_b128 v[198:201], v145 offset:512
	s_waitcnt lgkmcnt(4)
	s_waitcnt vmcnt(11)
	v_pk_add_f32 v[236:237], v[236:237], v[174:175] op_sel_hi:[1,0] neg_lo:[0,1] neg_hi:[0,1]
	v_pk_add_f32 v[238:239], v[238:239], v[174:175] op_sel_hi:[1,0] neg_lo:[0,1] neg_hi:[0,1]
	v_pk_mul_f32 v[236:237], v[236:237], v[174:175] op_sel:[0,1] op_sel_hi:[1,1]
	v_pk_mul_f32 v[238:239], v[238:239], v[174:175] op_sel:[0,1] op_sel_hi:[1,1]
	v_pk_fma_f32 v[236:237], v[236:237], v[154:155], v[162:163]
	v_pk_fma_f32 v[238:239], v[238:239], v[156:157], v[164:165]
	v_pk_fma_f32 v[186:187], v[236:237], s[16:17], v[186:187] op_sel_hi:[1,0,1]
	v_pk_fma_f32 v[188:189], v[238:239], s[16:17], v[188:189] op_sel_hi:[1,0,1]
	global_store_dwordx4 v140, v[186:189], s[60:61]
	global_load_dwordx4 v[236:239], v140, s[86:87] offset:512
	s_waitcnt vmcnt(12)
	v_pk_add_f32 v[240:241], v[240:241], v[176:177] op_sel_hi:[1,0] neg_lo:[0,1] neg_hi:[0,1]
	v_pk_add_f32 v[242:243], v[242:243], v[176:177] op_sel_hi:[1,0] neg_lo:[0,1] neg_hi:[0,1]
	v_pk_mul_f32 v[240:241], v[240:241], v[176:177] op_sel:[0,1] op_sel_hi:[1,1]
	v_pk_mul_f32 v[242:243], v[242:243], v[176:177] op_sel:[0,1] op_sel_hi:[1,1]
	v_pk_fma_f32 v[240:241], v[240:241], v[154:155], v[162:163]
	v_pk_fma_f32 v[242:243], v[242:243], v[156:157], v[164:165]
	v_pk_fma_f32 v[190:191], v[240:241], s[16:17], v[190:191] op_sel_hi:[1,0,1]
	v_pk_fma_f32 v[192:193], v[242:243], s[16:17], v[192:193] op_sel_hi:[1,0,1]
	global_store_dwordx4 v140, v[190:193], s[82:83]
	global_load_dwordx4 v[240:243], v140, s[66:67]
	ds_write_b128 v144, v[82:85]
	ds_write_b128 v144, v[78:81] offset:1024
	ds_read_b128 v[186:189], v145
	ds_read_b128 v[190:193], v145 offset:512
	s_waitcnt lgkmcnt(4)
	s_waitcnt vmcnt(15)
	v_pk_add_f32 v[244:245], v[244:245], v[174:175] op_sel_hi:[1,0] neg_lo:[0,1] neg_hi:[0,1]
	v_pk_add_f32 v[246:247], v[246:247], v[174:175] op_sel_hi:[1,0] neg_lo:[0,1] neg_hi:[0,1]
	v_pk_mul_f32 v[244:245], v[244:245], v[174:175] op_sel:[0,1] op_sel_hi:[1,1]
	v_pk_mul_f32 v[246:247], v[246:247], v[174:175] op_sel:[0,1] op_sel_hi:[1,1]
	v_pk_fma_f32 v[244:245], v[244:245], v[166:167], v[170:171]
	v_pk_fma_f32 v[246:247], v[246:247], v[168:169], v[172:173]
	v_pk_fma_f32 v[194:195], v[244:245], s[16:17], v[194:195] op_sel_hi:[1,0,1]
	v_pk_fma_f32 v[196:197], v[246:247], s[16:17], v[196:197] op_sel_hi:[1,0,1]
	global_store_dwordx4 v140, v[194:197], s[60:61] offset:512
	global_load_dwordx4 v[244:247], v140, s[88:89]
	s_waitcnt vmcnt(16)
	v_pk_add_f32 v[204:205], v[204:205], v[176:177] op_sel_hi:[1,0] neg_lo:[0,1] neg_hi:[0,1]
	v_pk_add_f32 v[206:207], v[206:207], v[176:177] op_sel_hi:[1,0] neg_lo:[0,1] neg_hi:[0,1]
	v_pk_mul_f32 v[204:205], v[204:205], v[176:177] op_sel:[0,1] op_sel_hi:[1,1]
	v_pk_mul_f32 v[206:207], v[206:207], v[176:177] op_sel:[0,1] op_sel_hi:[1,1]
	v_pk_fma_f32 v[204:205], v[204:205], v[166:167], v[170:171]
	v_pk_fma_f32 v[206:207], v[206:207], v[168:169], v[172:173]
	v_pk_fma_f32 v[198:199], v[204:205], s[16:17], v[198:199] op_sel_hi:[1,0,1]
	v_pk_fma_f32 v[200:201], v[206:207], s[16:17], v[200:201] op_sel_hi:[1,0,1]
	global_store_dwordx4 v140, v[198:201], s[82:83] offset:512
	global_load_dwordx4 v[204:207], v140, s[66:67] offset:512
	global_load_dwordx2 v[174:175], v141, s[76:77] offset:1024
	global_load_dwordx2 v[176:177], v141, s[76:77] offset:1088
	ds_write_b128 v144, v[74:77]
	ds_write_b128 v144, v[70:73] offset:1024
	ds_read_b128 v[194:197], v145
	ds_read_b128 v[198:201], v145 offset:512
	s_waitcnt lgkmcnt(4)
	s_waitcnt vmcnt(11)
	v_pk_add_f32 v[208:209], v[208:209], v[178:179] op_sel_hi:[1,0] neg_lo:[0,1] neg_hi:[0,1]
	v_pk_add_f32 v[210:211], v[210:211], v[178:179] op_sel_hi:[1,0] neg_lo:[0,1] neg_hi:[0,1]
	v_pk_mul_f32 v[208:209], v[208:209], v[178:179] op_sel:[0,1] op_sel_hi:[1,1]
	v_pk_mul_f32 v[210:211], v[210:211], v[178:179] op_sel:[0,1] op_sel_hi:[1,1]
	v_pk_fma_f32 v[208:209], v[208:209], v[154:155], v[162:163]
	v_pk_fma_f32 v[210:211], v[210:211], v[156:157], v[164:165]
	v_pk_fma_f32 v[186:187], v[208:209], s[16:17], v[186:187] op_sel_hi:[1,0,1]
	v_pk_fma_f32 v[188:189], v[210:211], s[16:17], v[188:189] op_sel_hi:[1,0,1]
	global_store_dwordx4 v140, v[186:189], s[62:63]
	global_load_dwordx4 v[208:211], v140, s[88:89] offset:512
	s_waitcnt vmcnt(12)
; DI bf16x4 pack4(float a, float b, float c, float d) { u32x2v u; u.x = pk2(a, b); u.y = pk2(c, d); return __builtin_bit_cast(bf16x4, u); }
; DI void ln_row_wave(const float* src, const float* g, const float* b, float* d32, bf16_t* db, int lane) {
;     ...
;   for (int i = 0; i < 4; ++i) {
;     float4 gg = reinterpret_cast<const float4*>(g)[lane + 64 * i], bb = reinterpret_cast<const float4*>(b)[lane + 64 * i];
;     float4 o;
;     o.x = (v[i].x - mu) * rstd * gg.x + bb.x; o.y = (v[i].y - mu) * rstd * gg.y + bb.y;
;     o.z = (v[i].z - mu) * rstd * gg.z + bb.z; o.w = (v[i].w - mu) * rstd * gg.w + bb.w;
;   DI void operator()(const f32x4 (&acc)[2][2][4][2], const pg8::Unit& u, int wr, int wc, int fr, int fq) const {
;     bf16_t* MERGED = (reinterpret_cast<bf16_t*>(p.ws + OFF_GA));
; #pragma unroll
;     for (int ai = 0; ai < 2; ++ai)
; #pragma unroll
;       for (int m = 0; m < 4; ++m) {
;         const int row = u.pm * 256 + 128 * ai + 64 * wr + 16 * m + fr;
; #pragma unroll
;         for (int bj = 0; bj < 2; ++bj)
; #pragma unroll
;           for (int n = 0; n < 2; ++n) {
;             const size_t idx = (size_t)row * 1024 + u.pn * 256 + 128 * bj + 32 * wc + 16 * n + 4 * fq;
;             const f32x4 a = acc[ai][bj][m][n];
;             if (MODE == 0) {
;               const unsigned g = *reinterpret_cast<const unsigned*>(reinterpret_cast<const unsigned char*>(p.ws + OFF_RB) + idx);
;               const float k = 1.f / 255.f;
;               st4(MERGED + idx, pack4((float)(g & 255u) * k * a[0], (float)((g >> 8) & 255u) * k * a[1], (float)((g >> 16) & 255u) * k * a[2], (float)(g >> 24) * k * a[3]));
;             } else {
;               f32x4 x = *reinterpret_cast<const f32x4*>(p.out + idx);
;               x = x * ALPHA + a;
;               *reinterpret_cast<f32x4*>(p.out + idx) = x;
;             }
	v_pk_add_f32 v[212:213], v[212:213], v[180:181] op_sel_hi:[1,0] neg_lo:[0,1] neg_hi:[0,1]
	v_pk_add_f32 v[214:215], v[214:215], v[180:181] op_sel_hi:[1,0] neg_lo:[0,1] neg_hi:[0,1]
	v_pk_mul_f32 v[212:213], v[212:213], v[180:181] op_sel:[0,1] op_sel_hi:[1,1]
	v_pk_mul_f32 v[214:215], v[214:215], v[180:181] op_sel:[0,1] op_sel_hi:[1,1]
	v_pk_fma_f32 v[212:213], v[212:213], v[154:155], v[162:163]
	v_pk_fma_f32 v[214:215], v[214:215], v[156:157], v[164:165]
	v_pk_fma_f32 v[190:191], v[212:213], s[16:17], v[190:191] op_sel_hi:[1,0,1]
	v_pk_fma_f32 v[192:193], v[214:215], s[16:17], v[192:193] op_sel_hi:[1,0,1]
	global_store_dwordx4 v140, v[190:193], s[84:85]
	global_load_dwordx4 v[212:215], v140, s[68:69]
	ds_write_b128 v144, v[66:69]
	ds_write_b128 v144, v[62:65] offset:1024
	ds_read_b128 v[186:189], v145
	ds_read_b128 v[190:193], v145 offset:512
	s_waitcnt lgkmcnt(4)
	s_waitcnt vmcnt(15)
	v_pk_add_f32 v[216:217], v[216:217], v[178:179] op_sel_hi:[1,0] neg_lo:[0,1] neg_hi:[0,1]
	v_pk_add_f32 v[218:219], v[218:219], v[178:179] op_sel_hi:[1,0] neg_lo:[0,1] neg_hi:[0,1]
	v_pk_mul_f32 v[216:217], v[216:217], v[178:179] op_sel:[0,1] op_sel_hi:[1,1]
	v_pk_mul_f32 v[218:219], v[218:219], v[178:179] op_sel:[0,1] op_sel_hi:[1,1]
	v_pk_fma_f32 v[216:217], v[216:217], v[166:167], v[170:171]
	v_pk_fma_f32 v[218:219], v[218:219], v[168:169], v[172:173]
	v_pk_fma_f32 v[194:195], v[216:217], s[16:17], v[194:195] op_sel_hi:[1,0,1]
	v_pk_fma_f32 v[196:197], v[218:219], s[16:17], v[196:197] op_sel_hi:[1,0,1]
	global_store_dwordx4 v140, v[194:197], s[62:63] offset:512
	global_load_dwordx4 v[216:219], v140, s[90:91]
	s_waitcnt vmcnt(16)
	v_pk_add_f32 v[220:221], v[220:221], v[180:181] op_sel_hi:[1,0] neg_lo:[0,1] neg_hi:[0,1]
	v_pk_add_f32 v[222:223], v[222:223], v[180:181] op_sel_hi:[1,0] neg_lo:[0,1] neg_hi:[0,1]
	v_pk_mul_f32 v[220:221], v[220:221], v[180:181] op_sel:[0,1] op_sel_hi:[1,1]
	v_pk_mul_f32 v[222:223], v[222:223], v[180:181] op_sel:[0,1] op_sel_hi:[1,1]
	v_pk_fma_f32 v[220:221], v[220:221], v[166:167], v[170:171]
	v_pk_fma_f32 v[222:223], v[222:223], v[168:169], v[172:173]
	v_pk_fma_f32 v[198:199], v[220:221], s[16:17], v[198:199] op_sel_hi:[1,0,1]
	v_pk_fma_f32 v[200:201], v[222:223], s[16:17], v[200:201] op_sel_hi:[1,0,1]
	global_store_dwordx4 v140, v[198:201], s[84:85] offset:512
	global_load_dwordx4 v[220:223], v140, s[68:69] offset:512
	global_load_dwordx2 v[178:179], v141, s[76:77] offset:1152
	global_load_dwordx2 v[180:181], v141, s[76:77] offset:1216
	ds_write_b128 v144, v[58:61]
	ds_write_b128 v144, v[54:57] offset:1024
	ds_read_b128 v[194:197], v145
	ds_read_b128 v[198:201], v145 offset:512
	s_waitcnt lgkmcnt(4)
	s_waitcnt vmcnt(11)
	v_pk_add_f32 v[224:225], v[224:225], v[174:175] op_sel_hi:[1,0] neg_lo:[0,1] neg_hi:[0,1]
	v_pk_add_f32 v[226:227], v[226:227], v[174:175] op_sel_hi:[1,0] neg_lo:[0,1] neg_hi:[0,1]
	v_pk_mul_f32 v[224:225], v[224:225], v[174:175] op_sel:[0,1] op_sel_hi:[1,1]
	v_pk_mul_f32 v[226:227], v[226:227], v[174:175] op_sel:[0,1] op_sel_hi:[1,1]
	v_pk_fma_f32 v[224:225], v[224:225], v[154:155], v[162:163]
	v_pk_fma_f32 v[226:227], v[226:227], v[156:157], v[164:165]
	v_pk_fma_f32 v[186:187], v[224:225], s[16:17], v[186:187] op_sel_hi:[1,0,1]
	v_pk_fma_f32 v[188:189], v[226:227], s[16:17], v[188:189] op_sel_hi:[1,0,1]
	global_store_dwordx4 v140, v[186:189], s[64:65]
	global_load_dwordx4 v[224:227], v140, s[90:91] offset:512
	s_waitcnt vmcnt(12)
	v_pk_add_f32 v[228:229], v[228:229], v[176:177] op_sel_hi:[1,0] neg_lo:[0,1] neg_hi:[0,1]
	v_pk_add_f32 v[230:231], v[230:231], v[176:177] op_sel_hi:[1,0] neg_lo:[0,1] neg_hi:[0,1]
	v_pk_mul_f32 v[228:229], v[228:229], v[176:177] op_sel:[0,1] op_sel_hi:[1,1]
	v_pk_mul_f32 v[230:231], v[230:231], v[176:177] op_sel:[0,1] op_sel_hi:[1,1]
	v_pk_fma_f32 v[228:229], v[228:229], v[154:155], v[162:163]
	v_pk_fma_f32 v[230:231], v[230:231], v[156:157], v[164:165]
	v_pk_fma_f32 v[190:191], v[228:229], s[16:17], v[190:191] op_sel_hi:[1,0,1]
	v_pk_fma_f32 v[192:193], v[230:231], s[16:17], v[192:193] op_sel_hi:[1,0,1]
	global_store_dwordx4 v140, v[190:193], s[86:87]
	global_load_dwordx4 v[228:231], v140, s[70:71]
	ds_write_b128 v144, v[50:53]
	ds_write_b128 v144, v[46:49] offset:1024
	ds_read_b128 v[186:189], v145
	ds_read_b128 v[190:193], v145 offset:512
	s_waitcnt lgkmcnt(4)
	s_waitcnt vmcnt(15)
	v_pk_add_f32 v[232:233], v[232:233], v[174:175] op_sel_hi:[1,0] neg_lo:[0,1] neg_hi:[0,1]
	v_pk_add_f32 v[234:235], v[234:235], v[174:175] op_sel_hi:[1,0] neg_lo:[0,1] neg_hi:[0,1]
	v_pk_mul_f32 v[232:233], v[232:233], v[174:175] op_sel:[0,1] op_sel_hi:[1,1]
	v_pk_mul_f32 v[234:235], v[234:235], v[174:175] op_sel:[0,1] op_sel_hi:[1,1]
	v_pk_fma_f32 v[232:233], v[232:233], v[166:167], v[170:171]
	v_pk_fma_f32 v[234:235], v[234:235], v[168:169], v[172:173]
	v_pk_fma_f32 v[194:195], v[232:233], s[16:17], v[194:195] op_sel_hi:[1,0,1]
	v_pk_fma_f32 v[196:197], v[234:235], s[16:17], v[196:197] op_sel_hi:[1,0,1]
	global_store_dwordx4 v140, v[194:197], s[64:65] offset:512
	global_load_dwordx4 v[232:235], v140, s[92:93]
	s_waitcnt vmcnt(16)
	v_pk_add_f32 v[236:237], v[236:237], v[176:177] op_sel_hi:[1,0] neg_lo:[0,1] neg_hi:[0,1]
	v_pk_add_f32 v[238:239], v[238:239], v[176:177] op_sel_hi:[1,0] neg_lo:[0,1] neg_hi:[0,1]
	v_pk_mul_f32 v[236:237], v[236:237], v[176:177] op_sel:[0,1] op_sel_hi:[1,1]
	v_pk_mul_f32 v[238:239], v[238:239], v[176:177] op_sel:[0,1] op_sel_hi:[1,1]
	v_pk_fma_f32 v[236:237], v[236:237], v[166:167], v[170:171]
	v_pk_fma_f32 v[238:239], v[238:239], v[168:169], v[172:173]
	v_pk_fma_f32 v[198:199], v[236:237], s[16:17], v[198:199] op_sel_hi:[1,0,1]
	v_pk_fma_f32 v[200:201], v[238:239], s[16:17], v[200:201] op_sel_hi:[1,0,1]
	global_store_dwordx4 v140, v[198:201], s[86:87] offset:512
	global_load_dwordx4 v[236:239], v140, s[70:71] offset:512
	global_load_dwordx2 v[174:175], v141, s[76:77] offset:1280
	global_load_dwordx2 v[176:177], v141, s[76:77] offset:1344
	ds_write_b128 v144, v[42:45]
	ds_write_b128 v144, v[38:41] offset:1024
	ds_read_b128 v[194:197], v145
	ds_read_b128 v[198:201], v145 offset:512
	s_waitcnt lgkmcnt(4)
; DI bf16x4 pack4(float a, float b, float c, float d) { u32x2v u; u.x = pk2(a, b); u.y = pk2(c, d); return __builtin_bit_cast(bf16x4, u); }
; DI void ln_row_wave(const float* src, const float* g, const float* b, float* d32, bf16_t* db, int lane) {
;     ...
;   for (int i = 0; i < 4; ++i) {
;     float4 gg = reinterpret_cast<const float4*>(g)[lane + 64 * i], bb = reinterpret_cast<const float4*>(b)[lane + 64 * i];
;     float4 o;
;     o.x = (v[i].x - mu) * rstd * gg.x + bb.x; o.y = (v[i].y - mu) * rstd * gg.y + bb.y;
;     o.z = (v[i].z - mu) * rstd * gg.z + bb.z; o.w = (v[i].w - mu) * rstd * gg.w + bb.w;
;   DI void operator()(const f32x4 (&acc)[2][2][4][2], const pg8::Unit& u, int wr, int wc, int fr, int fq) const {
;     bf16_t* MERGED = (reinterpret_cast<bf16_t*>(p.ws + OFF_GA));
; #pragma unroll
;     for (int ai = 0; ai < 2; ++ai)
; #pragma unroll
;       for (int m = 0; m < 4; ++m) {
;         const int row = u.pm * 256 + 128 * ai + 64 * wr + 16 * m + fr;
; #pragma unroll
;         for (int bj = 0; bj < 2; ++bj)
; #pragma unroll
;           for (int n = 0; n < 2; ++n) {
;             const size_t idx = (size_t)row * 1024 + u.pn * 256 + 128 * bj + 32 * wc + 16 * n + 4 * fq;
;             const f32x4 a = acc[ai][bj][m][n];
;             if (MODE == 0) {
;               const unsigned g = *reinterpret_cast<const unsigned*>(reinterpret_cast<const unsigned char*>(p.ws + OFF_RB) + idx);
;               const float k = 1.f / 255.f;
;               st4(MERGED + idx, pack4((float)(g & 255u) * k * a[0], (float)((g >> 8) & 255u) * k * a[1], (float)((g >> 16) & 255u) * k * a[2], (float)(g >> 24) * k * a[3]));
;             } else {
;               f32x4 x = *reinterpret_cast<const f32x4*>(p.out + idx);
;               x = x * ALPHA + a;
;               *reinterpret_cast<f32x4*>(p.out + idx) = x;
;             }
	s_waitcnt vmcnt(11)
	v_pk_add_f32 v[240:241], v[240:241], v[178:179] op_sel_hi:[1,0] neg_lo:[0,1] neg_hi:[0,1]
	v_pk_add_f32 v[242:243], v[242:243], v[178:179] op_sel_hi:[1,0] neg_lo:[0,1] neg_hi:[0,1]
	v_pk_mul_f32 v[240:241], v[240:241], v[178:179] op_sel:[0,1] op_sel_hi:[1,1]
	v_pk_mul_f32 v[242:243], v[242:243], v[178:179] op_sel:[0,1] op_sel_hi:[1,1]
	v_pk_fma_f32 v[240:241], v[240:241], v[154:155], v[162:163]
	v_pk_fma_f32 v[242:243], v[242:243], v[156:157], v[164:165]
	v_pk_fma_f32 v[186:187], v[240:241], s[16:17], v[186:187] op_sel_hi:[1,0,1]
	v_pk_fma_f32 v[188:189], v[242:243], s[16:17], v[188:189] op_sel_hi:[1,0,1]
	global_store_dwordx4 v140, v[186:189], s[66:67]
	global_load_dwordx4 v[240:243], v140, s[92:93] offset:512
	s_waitcnt vmcnt(12)
	v_pk_add_f32 v[244:245], v[244:245], v[180:181] op_sel_hi:[1,0] neg_lo:[0,1] neg_hi:[0,1]
	v_pk_add_f32 v[246:247], v[246:247], v[180:181] op_sel_hi:[1,0] neg_lo:[0,1] neg_hi:[0,1]
	v_pk_mul_f32 v[244:245], v[244:245], v[180:181] op_sel:[0,1] op_sel_hi:[1,1]
	v_pk_mul_f32 v[246:247], v[246:247], v[180:181] op_sel:[0,1] op_sel_hi:[1,1]
	v_pk_fma_f32 v[244:245], v[244:245], v[154:155], v[162:163]
	v_pk_fma_f32 v[246:247], v[246:247], v[156:157], v[164:165]
	v_pk_fma_f32 v[190:191], v[244:245], s[16:17], v[190:191] op_sel_hi:[1,0,1]
	v_pk_fma_f32 v[192:193], v[246:247], s[16:17], v[192:193] op_sel_hi:[1,0,1]
	global_store_dwordx4 v140, v[190:193], s[88:89]
	ds_write_b128 v144, v[34:37]
	ds_write_b128 v144, v[30:33] offset:1024
	ds_read_b128 v[186:189], v145
	ds_read_b128 v[190:193], v145 offset:512
	s_waitcnt lgkmcnt(4)
	s_waitcnt vmcnt(14)
	v_pk_add_f32 v[204:205], v[204:205], v[178:179] op_sel_hi:[1,0] neg_lo:[0,1] neg_hi:[0,1]
	v_pk_add_f32 v[206:207], v[206:207], v[178:179] op_sel_hi:[1,0] neg_lo:[0,1] neg_hi:[0,1]
	v_pk_mul_f32 v[204:205], v[204:205], v[178:179] op_sel:[0,1] op_sel_hi:[1,1]
	v_pk_mul_f32 v[206:207], v[206:207], v[178:179] op_sel:[0,1] op_sel_hi:[1,1]
	v_pk_fma_f32 v[204:205], v[204:205], v[166:167], v[170:171]
	v_pk_fma_f32 v[206:207], v[206:207], v[168:169], v[172:173]
	v_pk_fma_f32 v[194:195], v[204:205], s[16:17], v[194:195] op_sel_hi:[1,0,1]
	v_pk_fma_f32 v[196:197], v[206:207], s[16:17], v[196:197] op_sel_hi:[1,0,1]
	global_store_dwordx4 v140, v[194:197], s[66:67] offset:512
	s_waitcnt vmcnt(14)
	v_pk_add_f32 v[208:209], v[208:209], v[180:181] op_sel_hi:[1,0] neg_lo:[0,1] neg_hi:[0,1]
	v_pk_add_f32 v[210:211], v[210:211], v[180:181] op_sel_hi:[1,0] neg_lo:[0,1] neg_hi:[0,1]
	v_pk_mul_f32 v[208:209], v[208:209], v[180:181] op_sel:[0,1] op_sel_hi:[1,1]
	v_pk_mul_f32 v[210:211], v[210:211], v[180:181] op_sel:[0,1] op_sel_hi:[1,1]
	v_pk_fma_f32 v[208:209], v[208:209], v[166:167], v[170:171]
	v_pk_fma_f32 v[210:211], v[210:211], v[168:169], v[172:173]
	v_pk_fma_f32 v[198:199], v[208:209], s[16:17], v[198:199] op_sel_hi:[1,0,1]
	v_pk_fma_f32 v[200:201], v[210:211], s[16:17], v[200:201] op_sel_hi:[1,0,1]
	global_store_dwordx4 v140, v[198:201], s[88:89] offset:512
	global_load_dwordx2 v[178:179], v141, s[76:77] offset:1408
	global_load_dwordx2 v[180:181], v141, s[76:77] offset:1472
	ds_write_b128 v144, v[26:29]
	ds_write_b128 v144, v[22:25] offset:1024
	ds_read_b128 v[194:197], v145
	ds_read_b128 v[198:201], v145 offset:512
	s_waitcnt lgkmcnt(4)
	s_waitcnt vmcnt(8)
	v_pk_add_f32 v[212:213], v[212:213], v[174:175] op_sel_hi:[1,0] neg_lo:[0,1] neg_hi:[0,1]
	v_pk_add_f32 v[214:215], v[214:215], v[174:175] op_sel_hi:[1,0] neg_lo:[0,1] neg_hi:[0,1]
	v_pk_mul_f32 v[212:213], v[212:213], v[174:175] op_sel:[0,1] op_sel_hi:[1,1]
	v_pk_mul_f32 v[214:215], v[214:215], v[174:175] op_sel:[0,1] op_sel_hi:[1,1]
	v_pk_fma_f32 v[212:213], v[212:213], v[154:155], v[162:163]
	v_pk_fma_f32 v[214:215], v[214:215], v[156:157], v[164:165]
	v_pk_fma_f32 v[186:187], v[212:213], s[16:17], v[186:187] op_sel_hi:[1,0,1]
	v_pk_fma_f32 v[188:189], v[214:215], s[16:17], v[188:189] op_sel_hi:[1,0,1]
	global_store_dwordx4 v140, v[186:189], s[68:69]
	s_waitcnt vmcnt(8)
	v_pk_add_f32 v[216:217], v[216:217], v[176:177] op_sel_hi:[1,0] neg_lo:[0,1] neg_hi:[0,1]
	v_pk_add_f32 v[218:219], v[218:219], v[176:177] op_sel_hi:[1,0] neg_lo:[0,1] neg_hi:[0,1]
	v_pk_mul_f32 v[216:217], v[216:217], v[176:177] op_sel:[0,1] op_sel_hi:[1,1]
	v_pk_mul_f32 v[218:219], v[218:219], v[176:177] op_sel:[0,1] op_sel_hi:[1,1]
	v_pk_fma_f32 v[216:217], v[216:217], v[154:155], v[162:163]
	v_pk_fma_f32 v[218:219], v[218:219], v[156:157], v[164:165]
	v_pk_fma_f32 v[190:191], v[216:217], s[16:17], v[190:191] op_sel_hi:[1,0,1]
	v_pk_fma_f32 v[192:193], v[218:219], s[16:17], v[192:193] op_sel_hi:[1,0,1]
	global_store_dwordx4 v140, v[190:193], s[90:91]
	ds_write_b128 v144, v[12:15]
	ds_write_b128 v144, v[8:11] offset:1024
	ds_read_b128 v[186:189], v145
	ds_read_b128 v[190:193], v145 offset:512
	s_waitcnt lgkmcnt(4)
; DI bf16x4 pack4(float a, float b, float c, float d) { u32x2v u; u.x = pk2(a, b); u.y = pk2(c, d); return __builtin_bit_cast(bf16x4, u); }
; DI void ln_row_wave(const float* src, const float* g, const float* b, float* d32, bf16_t* db, int lane) {
;     ...
;   for (int i = 0; i < 4; ++i) {
;     float4 gg = reinterpret_cast<const float4*>(g)[lane + 64 * i], bb = reinterpret_cast<const float4*>(b)[lane + 64 * i];
;     float4 o;
;     o.x = (v[i].x - mu) * rstd * gg.x + bb.x; o.y = (v[i].y - mu) * rstd * gg.y + bb.y;
;     o.z = (v[i].z - mu) * rstd * gg.z + bb.z; o.w = (v[i].w - mu) * rstd * gg.w + bb.w;
;   DI void operator()(const f32x4 (&acc)[2][2][4][2], const pg8::Unit& u, int wr, int wc, int fr, int fq) const {
;     bf16_t* MERGED = (reinterpret_cast<bf16_t*>(p.ws + OFF_GA));
; #pragma unroll
;     for (int ai = 0; ai < 2; ++ai)
; #pragma unroll
;       for (int m = 0; m < 4; ++m) {
;         const int row = u.pm * 256 + 128 * ai + 64 * wr + 16 * m + fr;
; #pragma unroll
;         for (int bj = 0; bj < 2; ++bj)
; #pragma unroll
;           for (int n = 0; n < 2; ++n) {
;             const size_t idx = (size_t)row * 1024 + u.pn * 256 + 128 * bj + 32 * wc + 16 * n + 4 * fq;
;             const f32x4 a = acc[ai][bj][m][n];
;             if (MODE == 0) {
;               const unsigned g = *reinterpret_cast<const unsigned*>(reinterpret_cast<const unsigned char*>(p.ws + OFF_RB) + idx);
;               const float k = 1.f / 255.f;
;               st4(MERGED + idx, pack4((float)(g & 255u) * k * a[0], (float)((g >> 8) & 255u) * k * a[1], (float)((g >> 16) & 255u) * k * a[2], (float)(g >> 24) * k * a[3]));
;             } else {
;               f32x4 x = *reinterpret_cast<const f32x4*>(p.out + idx);
;               x = x * ALPHA + a;
;               *reinterpret_cast<f32x4*>(p.out + idx) = x;
;             }
	s_waitcnt vmcnt(10)
	v_pk_add_f32 v[220:221], v[220:221], v[174:175] op_sel_hi:[1,0] neg_lo:[0,1] neg_hi:[0,1]
	v_pk_add_f32 v[222:223], v[222:223], v[174:175] op_sel_hi:[1,0] neg_lo:[0,1] neg_hi:[0,1]
	v_pk_mul_f32 v[220:221], v[220:221], v[174:175] op_sel:[0,1] op_sel_hi:[1,1]
	v_pk_mul_f32 v[222:223], v[222:223], v[174:175] op_sel:[0,1] op_sel_hi:[1,1]
	v_pk_fma_f32 v[220:221], v[220:221], v[166:167], v[170:171]
	v_pk_fma_f32 v[222:223], v[222:223], v[168:169], v[172:173]
	v_pk_fma_f32 v[194:195], v[220:221], s[16:17], v[194:195] op_sel_hi:[1,0,1]
	v_pk_fma_f32 v[196:197], v[222:223], s[16:17], v[196:197] op_sel_hi:[1,0,1]
	global_store_dwordx4 v140, v[194:197], s[68:69] offset:512
	s_waitcnt vmcnt(10)
	v_pk_add_f32 v[224:225], v[224:225], v[176:177] op_sel_hi:[1,0] neg_lo:[0,1] neg_hi:[0,1]
	v_pk_add_f32 v[226:227], v[226:227], v[176:177] op_sel_hi:[1,0] neg_lo:[0,1] neg_hi:[0,1]
	v_pk_mul_f32 v[224:225], v[224:225], v[176:177] op_sel:[0,1] op_sel_hi:[1,1]
	v_pk_mul_f32 v[226:227], v[226:227], v[176:177] op_sel:[0,1] op_sel_hi:[1,1]
	v_pk_fma_f32 v[224:225], v[224:225], v[166:167], v[170:171]
	v_pk_fma_f32 v[226:227], v[226:227], v[168:169], v[172:173]
	v_pk_fma_f32 v[198:199], v[224:225], s[16:17], v[198:199] op_sel_hi:[1,0,1]
	v_pk_fma_f32 v[200:201], v[226:227], s[16:17], v[200:201] op_sel_hi:[1,0,1]
	global_store_dwordx4 v140, v[198:201], s[90:91] offset:512
	ds_write_b128 v144, v[4:7]
	ds_write_b128 v144, v[0:3] offset:1024
	ds_read_b128 v[194:197], v145
	ds_read_b128 v[198:201], v145 offset:512
	s_waitcnt lgkmcnt(4)
	s_waitcnt vmcnt(5)
	v_pk_add_f32 v[228:229], v[228:229], v[178:179] op_sel_hi:[1,0] neg_lo:[0,1] neg_hi:[0,1]
	v_pk_add_f32 v[230:231], v[230:231], v[178:179] op_sel_hi:[1,0] neg_lo:[0,1] neg_hi:[0,1]
	v_pk_mul_f32 v[228:229], v[228:229], v[178:179] op_sel:[0,1] op_sel_hi:[1,1]
	v_pk_mul_f32 v[230:231], v[230:231], v[178:179] op_sel:[0,1] op_sel_hi:[1,1]
	v_pk_fma_f32 v[228:229], v[228:229], v[154:155], v[162:163]
	v_pk_fma_f32 v[230:231], v[230:231], v[156:157], v[164:165]
	v_pk_fma_f32 v[186:187], v[228:229], s[16:17], v[186:187] op_sel_hi:[1,0,1]
	v_pk_fma_f32 v[188:189], v[230:231], s[16:17], v[188:189] op_sel_hi:[1,0,1]
	global_store_dwordx4 v140, v[186:189], s[70:71]
	s_waitcnt vmcnt(5)
	v_pk_add_f32 v[232:233], v[232:233], v[180:181] op_sel_hi:[1,0] neg_lo:[0,1] neg_hi:[0,1]
	v_pk_add_f32 v[234:235], v[234:235], v[180:181] op_sel_hi:[1,0] neg_lo:[0,1] neg_hi:[0,1]
	v_pk_mul_f32 v[232:233], v[232:233], v[180:181] op_sel:[0,1] op_sel_hi:[1,1]
	v_pk_mul_f32 v[234:235], v[234:235], v[180:181] op_sel:[0,1] op_sel_hi:[1,1]
	v_pk_fma_f32 v[232:233], v[232:233], v[154:155], v[162:163]
	v_pk_fma_f32 v[234:235], v[234:235], v[156:157], v[164:165]
	v_pk_fma_f32 v[190:191], v[232:233], s[16:17], v[190:191] op_sel_hi:[1,0,1]
	v_pk_fma_f32 v[192:193], v[234:235], s[16:17], v[192:193] op_sel_hi:[1,0,1]
	global_store_dwordx4 v140, v[190:193], s[92:93]
	s_waitcnt lgkmcnt(0)
	s_waitcnt vmcnt(7)
	v_pk_add_f32 v[236:237], v[236:237], v[178:179] op_sel_hi:[1,0] neg_lo:[0,1] neg_hi:[0,1]
	v_pk_add_f32 v[238:239], v[238:239], v[178:179] op_sel_hi:[1,0] neg_lo:[0,1] neg_hi:[0,1]
	v_pk_mul_f32 v[236:237], v[236:237], v[178:179] op_sel:[0,1] op_sel_hi:[1,1]
	v_pk_mul_f32 v[238:239], v[238:239], v[178:179] op_sel:[0,1] op_sel_hi:[1,1]
	v_pk_fma_f32 v[236:237], v[236:237], v[166:167], v[170:171]
	v_pk_fma_f32 v[238:239], v[238:239], v[168:169], v[172:173]
	v_pk_fma_f32 v[194:195], v[236:237], s[16:17], v[194:195] op_sel_hi:[1,0,1]
	v_pk_fma_f32 v[196:197], v[238:239], s[16:17], v[196:197] op_sel_hi:[1,0,1]
	global_store_dwordx4 v140, v[194:197], s[70:71] offset:512
	s_waitcnt vmcnt(7)
	v_pk_add_f32 v[240:241], v[240:241], v[180:181] op_sel_hi:[1,0] neg_lo:[0,1] neg_hi:[0,1]
	v_pk_add_f32 v[242:243], v[242:243], v[180:181] op_sel_hi:[1,0] neg_lo:[0,1] neg_hi:[0,1]
	v_pk_mul_f32 v[240:241], v[240:241], v[180:181] op_sel:[0,1] op_sel_hi:[1,1]
	v_pk_mul_f32 v[242:243], v[242:243], v[180:181] op_sel:[0,1] op_sel_hi:[1,1]
	v_pk_fma_f32 v[240:241], v[240:241], v[166:167], v[170:171]
	v_pk_fma_f32 v[242:243], v[242:243], v[168:169], v[172:173]
	v_pk_fma_f32 v[198:199], v[240:241], s[16:17], v[198:199] op_sel_hi:[1,0,1]
	v_pk_fma_f32 v[200:201], v[242:243], s[16:17], v[200:201] op_sel_hi:[1,0,1]
	global_store_dwordx4 v140, v[198:201], s[92:93] offset:512
	s_branch .Llz_join
